# grid barrier: census loads pipelined; acquire-side buffer_inv issued at arrival instead of after release (no cached loads in between)
# speedup vs baseline: 1.0054x; 1.0054x over previous
; __device__ __forceinline__ unsigned xb_add(unsigned* p, unsigned v) { return __hip_atomic_fetch_add(p, v, __ATOMIC_RELAXED, __HIP_MEMORY_SCOPE_AGENT); }
; __device__ __forceinline__ void xcd_barrier(const XcdBarrier& b) {
;     ...
;     if (threadIdx.x == 0) {
;         unsigned* bar = b.bar;
;         __builtin_amdgcn_s_waitcnt(0);
;         unsigned nloc = b.st[0], nx = b.st[1];
;         if (nloc == 0u) { xcd_barrier_complete(bar, b.x, nloc, nx); b.st[0] = nloc; b.st[1] = nx; }
;         const unsigned old = xb_add(&bar[XB_XSUB(b.x)], 1u);
;         const unsigned gen = old / nloc;
;         if (old + 1u == (gen + 1u) * nloc) {
.LBB0_756:
	buffer_inv sc1
	s_mov_b64 s[38:39], exec
	v_mbcnt_lo_u32_b32 v0, s38, 0
	v_mbcnt_hi_u32_b32 v0, s39, v0
	v_cmp_eq_u32_e32 vcc, 0, v0
	s_and_saveexec_b64 s[34:35], vcc
	s_cbranch_execz .LBB0_758
	s_bcnt1_i32_b64 s2, s[38:39]
	v_readlane_b32 s6, v252, 38
	v_mov_b32_e32 v4, s2
	v_readlane_b32 s7, v252, 39
	s_nop 4
	global_atomic_add v4, v1, v4, s[6:7] sc0

; __device__ __forceinline__ unsigned xb_ld(unsigned* p)              { return __hip_atomic_load(p, __ATOMIC_RELAXED, __HIP_MEMORY_SCOPE_AGENT); }
; #define XB_SPIN(cond, bar) do { unsigned _sp = 0; while (cond) { __builtin_amdgcn_s_sleep(1); \
;     if ((++_sp & 255u) == 0u) { if (xb_ld(&(bar)[XB_TMO])) break; if (_sp > XB_SPIN_CAP) { atomicAdd(&(bar)[XB_TMO], 1u); break; } } } } while (0)
; __device__ __forceinline__ void xcd_barrier(const XcdBarrier& b) {
;     ...
;             XB_SPIN(xb_ld(&bar[XB_XGEN(b.x)]) == gen, bar);
;             __builtin_amdgcn_fence(__ATOMIC_ACQUIRE, "agent");
;             asm volatile("s_waitcnt vmcnt(0)" ::: "memory");
.LBB0_771:
	s_or_b64 exec, exec, s[40:41]
	s_waitcnt vmcnt(0)
	s_waitcnt vmcnt(0)

; __device__ __forceinline__ unsigned xb_ld(unsigned* p)              { return __hip_atomic_load(p, __ATOMIC_RELAXED, __HIP_MEMORY_SCOPE_AGENT); }
; __device__ __forceinline__ unsigned xb_add(unsigned* p, unsigned v) { return __hip_atomic_fetch_add(p, v, __ATOMIC_RELAXED, __HIP_MEMORY_SCOPE_AGENT); }
; #define XB_SPIN(cond, bar) do { unsigned _sp = 0; while (cond) { __builtin_amdgcn_s_sleep(1); \
;     if ((++_sp & 255u) == 0u) { if (xb_ld(&(bar)[XB_TMO])) break; if (_sp > XB_SPIN_CAP) { atomicAdd(&(bar)[XB_TMO], 1u); break; } } } } while (0)
; __device__ __forceinline__ void xcd_barrier(const XcdBarrier& b) {
;     ...
;             if (og + 1u == (tg + 1u) * nx) xb_add(&bar[XB_TOPGEN], 1u);
;             else XB_SPIN(xb_ld(&bar[XB_TOPGEN]) == tg, bar);
;             __builtin_amdgcn_fence(__ATOMIC_ACQUIRE, "agent");
;             xb_add(&bar[XB_XGEN(b.x)], 1u);
.LBB0_789:
	s_or_b64 exec, exec, s[34:35]
	s_mov_b64 s[34:35], exec
	v_mbcnt_lo_u32_b32 v0, s34, 0
	v_mbcnt_hi_u32_b32 v0, s35, v0
	v_cmp_eq_u32_e32 vcc, 0, v0
	s_waitcnt vmcnt(0)
	s_and_saveexec_b64 s[38:39], vcc
	s_cbranch_execz .LBB0_791
	s_bcnt1_i32_b64 s2, s[34:35]
	v_readlane_b32 s6, v252, 40
	v_mov_b32_e32 v0, s2
	v_readlane_b32 s7, v252, 41
	s_nop 4
	global_atomic_add v1, v0, s[6:7]

; __device__ __forceinline__ unsigned xb_add(unsigned* p, unsigned v) { return __hip_atomic_fetch_add(p, v, __ATOMIC_RELAXED, __HIP_MEMORY_SCOPE_AGENT); }
; __device__ __forceinline__ void xcd_barrier(const XcdBarrier& b) {
;     ...
;     if (threadIdx.x == 0) {
;         unsigned* bar = b.bar;
;         __builtin_amdgcn_s_waitcnt(0);
;         unsigned nloc = b.st[0], nx = b.st[1];
;         if (nloc == 0u) { xcd_barrier_complete(bar, b.x, nloc, nx); b.st[0] = nloc; b.st[1] = nx; }
;         const unsigned old = xb_add(&bar[XB_XSUB(b.x)], 1u);
;         const unsigned gen = old / nloc;
;         if (old + 1u == (gen + 1u) * nloc) {
.LBB0_834:
	buffer_inv sc1
	s_mov_b64 s[42:43], exec
	v_mbcnt_lo_u32_b32 v0, s42, 0
	v_mbcnt_hi_u32_b32 v0, s43, v0
	v_cmp_eq_u32_e32 vcc, 0, v0
	s_and_saveexec_b64 s[34:35], vcc
	s_cbranch_execz .LBB0_836
	s_bcnt1_i32_b64 s2, s[42:43]
	v_readlane_b32 s6, v252, 38
	v_mov_b32_e32 v4, s2
	v_readlane_b32 s7, v252, 39
	s_nop 4
	global_atomic_add v4, v1, v4, s[6:7] sc0

; __device__ __forceinline__ unsigned xb_ld(unsigned* p)              { return __hip_atomic_load(p, __ATOMIC_RELAXED, __HIP_MEMORY_SCOPE_AGENT); }
; #define XB_SPIN(cond, bar) do { unsigned _sp = 0; while (cond) { __builtin_amdgcn_s_sleep(1); \
;     if ((++_sp & 255u) == 0u) { if (xb_ld(&(bar)[XB_TMO])) break; if (_sp > XB_SPIN_CAP) { atomicAdd(&(bar)[XB_TMO], 1u); break; } } } } while (0)
; __device__ __forceinline__ void xcd_barrier(const XcdBarrier& b) {
;     ...
;             XB_SPIN(xb_ld(&bar[XB_XGEN(b.x)]) == gen, bar);
;             __builtin_amdgcn_fence(__ATOMIC_ACQUIRE, "agent");
;             asm volatile("s_waitcnt vmcnt(0)" ::: "memory");
.LBB0_849:
	s_or_b64 exec, exec, s[44:45]
	s_waitcnt vmcnt(0)
	s_waitcnt vmcnt(0)

; __device__ __forceinline__ unsigned xb_ld(unsigned* p)              { return __hip_atomic_load(p, __ATOMIC_RELAXED, __HIP_MEMORY_SCOPE_AGENT); }
; __device__ __forceinline__ unsigned xb_add(unsigned* p, unsigned v) { return __hip_atomic_fetch_add(p, v, __ATOMIC_RELAXED, __HIP_MEMORY_SCOPE_AGENT); }
; #define XB_SPIN(cond, bar) do { unsigned _sp = 0; while (cond) { __builtin_amdgcn_s_sleep(1); \
;     if ((++_sp & 255u) == 0u) { if (xb_ld(&(bar)[XB_TMO])) break; if (_sp > XB_SPIN_CAP) { atomicAdd(&(bar)[XB_TMO], 1u); break; } } } } while (0)
; __device__ __forceinline__ void xcd_barrier(const XcdBarrier& b) {
;     ...
;             if (og + 1u == (tg + 1u) * nx) xb_add(&bar[XB_TOPGEN], 1u);
;             else XB_SPIN(xb_ld(&bar[XB_TOPGEN]) == tg, bar);
;             __builtin_amdgcn_fence(__ATOMIC_ACQUIRE, "agent");
;             xb_add(&bar[XB_XGEN(b.x)], 1u);
.LBB0_867:
	s_or_b64 exec, exec, s[34:35]
	s_mov_b64 s[34:35], exec
	v_mbcnt_lo_u32_b32 v0, s34, 0
	v_mbcnt_hi_u32_b32 v0, s35, v0
	v_cmp_eq_u32_e32 vcc, 0, v0
	s_waitcnt vmcnt(0)
	s_and_saveexec_b64 s[44:45], vcc
	s_cbranch_execz .LBB0_869
	s_bcnt1_i32_b64 s2, s[34:35]
	v_readlane_b32 s6, v252, 40
	v_mov_b32_e32 v0, s2
	v_readlane_b32 s7, v252, 41
	s_nop 4
	global_atomic_add v1, v0, s[6:7]

; __device__ __forceinline__ unsigned xb_add(unsigned* p, unsigned v) { return __hip_atomic_fetch_add(p, v, __ATOMIC_RELAXED, __HIP_MEMORY_SCOPE_AGENT); }
; __device__ __forceinline__ void xcd_barrier(const XcdBarrier& b) {
;     ...
;     if (threadIdx.x == 0) {
;         unsigned* bar = b.bar;
;         __builtin_amdgcn_s_waitcnt(0);
;         unsigned nloc = b.st[0], nx = b.st[1];
;         if (nloc == 0u) { xcd_barrier_complete(bar, b.x, nloc, nx); b.st[0] = nloc; b.st[1] = nx; }
;         const unsigned old = xb_add(&bar[XB_XSUB(b.x)], 1u);
;         const unsigned gen = old / nloc;
;         if (old + 1u == (gen + 1u) * nloc) {
.LBB0_1764:
	buffer_inv sc1
	s_mov_b64 s[24:25], exec
	v_mbcnt_lo_u32_b32 v0, s24, 0
	v_mbcnt_hi_u32_b32 v0, s25, v0
	v_cmp_eq_u32_e32 vcc, 0, v0
	s_and_saveexec_b64 s[20:21], vcc
	s_cbranch_execz .LBB0_1766
	s_bcnt1_i32_b64 s2, s[24:25]
	v_readlane_b32 s6, v252, 38
	v_mov_b32_e32 v4, s2
	v_readlane_b32 s7, v252, 39
	s_nop 4
	global_atomic_add v4, v1, v4, s[6:7] sc0

; __device__ __forceinline__ unsigned xb_ld(unsigned* p)              { return __hip_atomic_load(p, __ATOMIC_RELAXED, __HIP_MEMORY_SCOPE_AGENT); }
; #define XB_SPIN(cond, bar) do { unsigned _sp = 0; while (cond) { __builtin_amdgcn_s_sleep(1); \
;     if ((++_sp & 255u) == 0u) { if (xb_ld(&(bar)[XB_TMO])) break; if (_sp > XB_SPIN_CAP) { atomicAdd(&(bar)[XB_TMO], 1u); break; } } } } while (0)
; __device__ __forceinline__ void xcd_barrier(const XcdBarrier& b) {
;     ...
;             XB_SPIN(xb_ld(&bar[XB_XGEN(b.x)]) == gen, bar);
;             __builtin_amdgcn_fence(__ATOMIC_ACQUIRE, "agent");
;             asm volatile("s_waitcnt vmcnt(0)" ::: "memory");
.LBB0_1779:
	s_or_b64 exec, exec, s[24:25]
	s_waitcnt vmcnt(0)
	s_waitcnt vmcnt(0)

; __device__ __forceinline__ unsigned xb_ld(unsigned* p)              { return __hip_atomic_load(p, __ATOMIC_RELAXED, __HIP_MEMORY_SCOPE_AGENT); }
; __device__ __forceinline__ unsigned xb_add(unsigned* p, unsigned v) { return __hip_atomic_fetch_add(p, v, __ATOMIC_RELAXED, __HIP_MEMORY_SCOPE_AGENT); }
; #define XB_SPIN(cond, bar) do { unsigned _sp = 0; while (cond) { __builtin_amdgcn_s_sleep(1); \
;     if ((++_sp & 255u) == 0u) { if (xb_ld(&(bar)[XB_TMO])) break; if (_sp > XB_SPIN_CAP) { atomicAdd(&(bar)[XB_TMO], 1u); break; } } } } while (0)
; __device__ __forceinline__ void xcd_barrier(const XcdBarrier& b) {
;     ...
;             if (og + 1u == (tg + 1u) * nx) xb_add(&bar[XB_TOPGEN], 1u);
;             else XB_SPIN(xb_ld(&bar[XB_TOPGEN]) == tg, bar);
;             __builtin_amdgcn_fence(__ATOMIC_ACQUIRE, "agent");
;             xb_add(&bar[XB_XGEN(b.x)], 1u);
.LBB0_1797:
	s_or_b64 exec, exec, s[20:21]
	s_mov_b64 s[20:21], exec
	v_mbcnt_lo_u32_b32 v0, s20, 0
	v_mbcnt_hi_u32_b32 v0, s21, v0
	v_cmp_eq_u32_e32 vcc, 0, v0
	s_waitcnt vmcnt(0)
	s_and_saveexec_b64 s[24:25], vcc
	s_cbranch_execnz .LBB0_1798
	s_getpc_b64 s[98:99]
